# v33 + warm-up of the layer's bf16 per-layer-embedding input slice (A of the K=256 ple GEMM) during the up tiles
# baseline (speedup 1.0000x reference)
;     __device__ void init(int M, int N, int G_, int c_) { nM = M / BM; nN = N / BM; nwg = nM * nN; G = launder_s(G_); c = launder_s(c_); }
; __global__ void __launch_bounds__(NTHR, 2) mk_fwd(Args args) {
;     ...
;             { pg8::Gemm g{HB0, (const bf16_t*)(wl + WOFF_UP), T, DFF, D, D, D, 0, 0}; pg8::StaticOrder S; S.init(T, DFF, G, bid); pg8::EpiBf16<2> E{UP, DFF, nullptr}; pg8::gemm_phase(lds, g, S, E); }
;             if (l != 3) { pg8::Gemm g{PBF + (size_t)l * T * PLE, (const bf16_t*)(wl + WOFF_PLE), T, D, PLE, PLE, PLE, 0, 0}; pg8::StaticOrder S; S.init(T, D, G, bid); pg8::EpiBf16<0> E{PP, D, nullptr}; pg8::gemm_phase(lds, g, S, E); }
.Lwpf_D:
	s_cmp_ge_u32 s74, 64
	s_cbranch_scc1 .Lwpf_P
	s_lshl_b32 s100, s74, 9
	v_add_u32_e32 v146, s100, v246
	v_lshlrev_b32_e32 v146, 7, v146
	v_readlane_b32 s100, v255, 42
	s_nop 3
	s_lshl_b32 s101, s100, 22
	s_add_u32 s101, s101, 0x1db00000
	s_add_u32 s100, s38, s101
	s_addc_u32 s101, s39, 0
	s_mov_b32 m0, 0x21000
	s_nop 0
	global_load_lds_dword v146, s[100:101]
